# v059: v056 + accumulator zeroing between GEMM units with v_mov_b64 pairs (half the VALU instructions)
# baseline (speedup 1.0000x reference)
.LBB0_338:
	s_ashr_i32 s29, s28, 31
	v_cmp_lt_i64_e64 s[42:43], s[34:35], 64
	s_lshl_b64 s[34:35], s[28:29], 19
	s_add_u32 s34, s48, s34
	s_addc_u32 s35, s49, s35
	s_and_b64 s[36:37], s[42:43], exec
	s_cselect_b32 s1, s35, s39
	s_cselect_b32 s7, s34, s38
	s_ashr_i32 s31, s30, 31
	s_lshl_b64 s[36:37], s[30:31], 19
	s_add_u32 s36, s50, s36
	s_addc_u32 s37, s51, s37
	s_and_b64 s[42:43], s[42:43], exec
	s_cselect_b32 s29, s37, s41
	s_cselect_b32 s31, s36, s40
	s_add_u32 s65, s40, 0x100
	v_mov_b32_e32 v2, 0
	s_addc_u32 s66, s41, 0
	s_mov_b32 s67, -2
	v_mov_b32_e32 v3, v2
	v_mov_b32_e32 v4, v2
	v_mov_b32_e32 v5, v2
	v_mov_b32_e32 v6, v2
	v_mov_b32_e32 v7, v2
	v_mov_b32_e32 v8, v2
	v_mov_b32_e32 v9, v2
	s_waitcnt vmcnt(0)
	v_mov_b64_e32 v[18:19], 0
	v_mov_b64_e32 v[20:21], 0
	v_mov_b64_e32 v[22:23], 0
	v_mov_b64_e32 v[24:25], 0
	v_mov_b64_e32 v[34:35], 0
	v_mov_b64_e32 v[36:37], 0
	v_mov_b64_e32 v[38:39], 0
	v_mov_b64_e32 v[40:41], 0
	v_mov_b64_e32 v[50:51], 0
	v_mov_b64_e32 v[52:53], 0
	v_mov_b64_e32 v[54:55], 0
	v_mov_b64_e32 v[56:57], 0
	v_mov_b64_e32 v[10:11], 0
	v_mov_b64_e32 v[12:13], 0
	v_mov_b64_e32 v[14:15], 0
	v_mov_b64_e32 v[16:17], 0
	v_mov_b64_e32 v[26:27], 0
	v_mov_b64_e32 v[28:29], 0
	v_mov_b64_e32 v[30:31], 0
	v_mov_b64_e32 v[32:33], 0
	v_mov_b64_e32 v[42:43], 0
	v_mov_b64_e32 v[44:45], 0
	v_mov_b64_e32 v[46:47], 0
	v_mov_b64_e32 v[48:49], 0
	v_mov_b64_e32 v[58:59], 0
	v_mov_b64_e32 v[60:61], 0
	v_mov_b64_e32 v[62:63], 0
	v_mov_b64_e32 v[64:65], 0
	v_mov_b64_e32 v[66:67], 0
	v_mov_b64_e32 v[68:69], 0
	v_mov_b64_e32 v[70:71], 0
	v_mov_b64_e32 v[72:73], 0
	v_mov_b64_e32 v[82:83], 0
	v_mov_b64_e32 v[84:85], 0
	v_mov_b64_e32 v[86:87], 0
	v_mov_b64_e32 v[88:89], 0
	v_mov_b64_e32 v[98:99], 0
	v_mov_b64_e32 v[100:101], 0
	v_mov_b64_e32 v[102:103], 0
	v_mov_b64_e32 v[104:105], 0
	v_mov_b64_e32 v[114:115], 0
	v_mov_b64_e32 v[116:117], 0
	v_mov_b64_e32 v[118:119], 0
	v_mov_b64_e32 v[120:121], 0
	v_mov_b64_e32 v[74:75], 0
	v_mov_b64_e32 v[76:77], 0
	v_mov_b64_e32 v[78:79], 0
	v_mov_b64_e32 v[80:81], 0
	v_mov_b64_e32 v[90:91], 0
	v_mov_b64_e32 v[92:93], 0
	v_mov_b64_e32 v[94:95], 0
	v_mov_b64_e32 v[96:97], 0
	v_mov_b64_e32 v[106:107], 0
	v_mov_b64_e32 v[108:109], 0
	v_mov_b64_e32 v[110:111], 0
	v_mov_b64_e32 v[112:113], 0
	v_mov_b64_e32 v[122:123], 0
	v_mov_b64_e32 v[124:125], 0
	v_mov_b64_e32 v[126:127], 0
	v_mov_b64_e32 v[128:129], 0

.LBB0_393:
	s_ashr_i32 s13, s12, 31
	s_lshl_b64 s[18:19], s[12:13], 17
	s_add_u32 s18, s45, s18
	s_addc_u32 s19, s46, s19
	s_and_b64 s[22:23], s[22:23], exec
	v_mov_b32_e32 v2, 0
	s_cselect_b32 s1, s19, s7
	s_cselect_b32 s13, s18, s6
	s_mov_b64 s[24:25], 0
	s_mov_b64 s[22:23], -1
	s_mov_b64 s[28:29], 0
	s_waitcnt lgkmcnt(0)
	v_mov_b32_e32 v3, v2
	v_mov_b64_e32 v[4:5], 0
	v_mov_b64_e32 v[6:7], 0
	v_mov_b64_e32 v[8:9], 0
	v_mov_b64_e32 v[18:19], 0
	v_mov_b64_e32 v[20:21], 0
	v_mov_b64_e32 v[22:23], 0
	v_mov_b64_e32 v[24:25], 0
	v_mov_b64_e32 v[34:35], 0
	v_mov_b64_e32 v[36:37], 0
	v_mov_b64_e32 v[38:39], 0
	v_mov_b64_e32 v[40:41], 0
	v_mov_b64_e32 v[50:51], 0
	v_mov_b64_e32 v[52:53], 0
	v_mov_b64_e32 v[54:55], 0
	v_mov_b64_e32 v[56:57], 0
	v_mov_b64_e32 v[10:11], 0
	v_mov_b64_e32 v[12:13], 0
	v_mov_b64_e32 v[14:15], 0
	v_mov_b64_e32 v[16:17], 0
	v_mov_b64_e32 v[26:27], 0
	v_mov_b64_e32 v[28:29], 0
	v_mov_b64_e32 v[30:31], 0
	v_mov_b64_e32 v[32:33], 0
	v_mov_b64_e32 v[42:43], 0
	v_mov_b64_e32 v[44:45], 0
	v_mov_b64_e32 v[46:47], 0
	v_mov_b64_e32 v[48:49], 0
	v_mov_b64_e32 v[58:59], 0
	v_mov_b64_e32 v[60:61], 0
	v_mov_b64_e32 v[62:63], 0
	v_mov_b64_e32 v[64:65], 0
	v_mov_b64_e32 v[66:67], 0
	v_mov_b64_e32 v[68:69], 0
	v_mov_b64_e32 v[70:71], 0
	v_mov_b64_e32 v[72:73], 0
	v_mov_b64_e32 v[82:83], 0
	v_mov_b64_e32 v[84:85], 0
	v_mov_b64_e32 v[86:87], 0
	v_mov_b64_e32 v[88:89], 0
	v_mov_b64_e32 v[98:99], 0
	v_mov_b64_e32 v[100:101], 0
	v_mov_b64_e32 v[102:103], 0
	v_mov_b64_e32 v[104:105], 0
	v_mov_b64_e32 v[114:115], 0
	v_mov_b64_e32 v[116:117], 0
	v_mov_b64_e32 v[118:119], 0
	v_mov_b64_e32 v[120:121], 0
	v_mov_b64_e32 v[74:75], 0
	v_mov_b64_e32 v[76:77], 0
	v_mov_b64_e32 v[78:79], 0
	v_mov_b64_e32 v[80:81], 0
	v_mov_b64_e32 v[90:91], 0
	v_mov_b64_e32 v[92:93], 0
	v_mov_b64_e32 v[94:95], 0
	v_mov_b64_e32 v[96:97], 0
	v_mov_b64_e32 v[106:107], 0
	v_mov_b64_e32 v[108:109], 0
	v_mov_b64_e32 v[110:111], 0
	v_mov_b64_e32 v[112:113], 0
	v_mov_b64_e32 v[122:123], 0
	v_mov_b64_e32 v[124:125], 0
	v_mov_b64_e32 v[126:127], 0
	v_mov_b64_e32 v[128:129], 0
	s_waitcnt vmcnt(0)

.LBB0_504:
	s_ashr_i32 s43, s42, 31
	v_cmp_lt_i64_e32 vcc, s[20:21], v[140:141]
	s_lshl_b64 s[20:21], s[42:43], 19
	s_add_u32 s44, s56, s20
	s_addc_u32 s45, s57, s21
	s_and_b64 s[20:21], vcc, exec
	s_cselect_b32 s1, s45, s17
	s_cselect_b32 s9, s44, s16
	s_ashr_i32 s41, s40, 31
	s_lshl_b64 s[20:21], s[40:41], 19
	s_add_u32 s46, s63, s20
	s_addc_u32 s47, s72, s21
	s_and_b64 s[20:21], vcc, exec
	s_cselect_b32 s41, s47, s19
	s_cselect_b32 s43, s46, s18
	s_add_u32 s52, s18, 0x100
	v_mov_b32_e32 v4, 0
	s_addc_u32 s53, s19, 0
	s_mov_b32 s62, -2
	s_waitcnt lgkmcnt(0)
	v_mov_b32_e32 v5, v4
	v_mov_b64_e32 v[6:7], 0
	v_mov_b64_e32 v[8:9], 0
	v_mov_b64_e32 v[10:11], 0
	v_mov_b64_e32 v[20:21], 0
	v_mov_b64_e32 v[22:23], 0
	v_mov_b64_e32 v[24:25], 0
	v_mov_b64_e32 v[26:27], 0
	v_mov_b64_e32 v[36:37], 0
	v_mov_b64_e32 v[38:39], 0
	v_mov_b64_e32 v[40:41], 0
	v_mov_b64_e32 v[42:43], 0
	v_mov_b64_e32 v[52:53], 0
	v_mov_b64_e32 v[54:55], 0
	v_mov_b64_e32 v[56:57], 0
	v_mov_b64_e32 v[58:59], 0
	v_mov_b64_e32 v[12:13], 0
	v_mov_b64_e32 v[14:15], 0
	v_mov_b64_e32 v[16:17], 0
	v_mov_b64_e32 v[18:19], 0
	v_mov_b64_e32 v[28:29], 0
	v_mov_b64_e32 v[30:31], 0
	v_mov_b64_e32 v[32:33], 0
	v_mov_b64_e32 v[34:35], 0
	v_mov_b64_e32 v[44:45], 0
	v_mov_b64_e32 v[46:47], 0
	v_mov_b64_e32 v[48:49], 0
	v_mov_b64_e32 v[50:51], 0
	v_mov_b64_e32 v[60:61], 0
	v_mov_b64_e32 v[62:63], 0
	v_mov_b64_e32 v[64:65], 0
	v_mov_b64_e32 v[66:67], 0
	v_mov_b64_e32 v[68:69], 0
	v_mov_b64_e32 v[70:71], 0
	v_mov_b64_e32 v[72:73], 0
	v_mov_b64_e32 v[74:75], 0
	v_mov_b64_e32 v[84:85], 0
	v_mov_b64_e32 v[86:87], 0
	v_mov_b64_e32 v[88:89], 0
	v_mov_b64_e32 v[90:91], 0
	v_mov_b64_e32 v[100:101], 0
	v_mov_b64_e32 v[102:103], 0
	v_mov_b64_e32 v[104:105], 0
	v_mov_b64_e32 v[106:107], 0
	v_mov_b64_e32 v[116:117], 0
	v_mov_b64_e32 v[118:119], 0
	v_mov_b64_e32 v[120:121], 0
	v_mov_b64_e32 v[122:123], 0
	v_mov_b64_e32 v[76:77], 0
	v_mov_b64_e32 v[78:79], 0
	v_mov_b64_e32 v[80:81], 0
	v_mov_b64_e32 v[82:83], 0
	v_mov_b64_e32 v[92:93], 0
	v_mov_b64_e32 v[94:95], 0
	v_mov_b64_e32 v[96:97], 0
	v_mov_b64_e32 v[98:99], 0
	v_mov_b64_e32 v[108:109], 0
	v_mov_b64_e32 v[110:111], 0
	v_mov_b64_e32 v[112:113], 0
	v_mov_b64_e32 v[114:115], 0
	v_mov_b64_e32 v[124:125], 0
	v_mov_b64_e32 v[126:127], 0
	v_mov_b64_e32 v[128:129], 0
	v_mov_b64_e32 v[130:131], 0

.LBB0_653:
	s_ashr_i32 s17, s16, 31
	s_lshl_b64 s[20:21], s[16:17], 17
	s_add_u32 s20, s48, s20
	s_addc_u32 s21, s49, s21
	s_and_b64 s[24:25], s[24:25], exec
	v_mov_b32_e32 v4, 0
	s_cselect_b32 s17, s21, s1
	s_cselect_b32 s23, s20, s0
	s_mov_b64 s[26:27], 0
	s_mov_b64 s[24:25], -1
	s_mov_b64 s[28:29], 0
	s_waitcnt lgkmcnt(0)
	v_mov_b32_e32 v5, v4
	v_mov_b64_e32 v[6:7], 0
	v_mov_b64_e32 v[8:9], 0
	v_mov_b64_e32 v[10:11], 0
	v_mov_b64_e32 v[20:21], 0
	v_mov_b64_e32 v[22:23], 0
	v_mov_b64_e32 v[24:25], 0
	v_mov_b64_e32 v[26:27], 0
	v_mov_b64_e32 v[36:37], 0
	v_mov_b64_e32 v[38:39], 0
	v_mov_b64_e32 v[40:41], 0
	v_mov_b64_e32 v[42:43], 0
	v_mov_b64_e32 v[52:53], 0
	v_mov_b64_e32 v[54:55], 0
	v_mov_b64_e32 v[56:57], 0
	v_mov_b64_e32 v[58:59], 0
	v_mov_b64_e32 v[12:13], 0
	v_mov_b64_e32 v[14:15], 0
	v_mov_b64_e32 v[16:17], 0
	v_mov_b64_e32 v[18:19], 0
	v_mov_b64_e32 v[28:29], 0
	v_mov_b64_e32 v[30:31], 0
	v_mov_b64_e32 v[32:33], 0
	v_mov_b64_e32 v[34:35], 0
	v_mov_b64_e32 v[44:45], 0
	v_mov_b64_e32 v[46:47], 0
	v_mov_b64_e32 v[48:49], 0
	v_mov_b64_e32 v[50:51], 0
	v_mov_b64_e32 v[60:61], 0
	v_mov_b64_e32 v[62:63], 0
	v_mov_b64_e32 v[64:65], 0
	v_mov_b64_e32 v[66:67], 0
	v_mov_b64_e32 v[68:69], 0
	v_mov_b64_e32 v[70:71], 0
	v_mov_b64_e32 v[72:73], 0
	v_mov_b64_e32 v[74:75], 0
	v_mov_b64_e32 v[84:85], 0
	v_mov_b64_e32 v[86:87], 0
	v_mov_b64_e32 v[88:89], 0
	v_mov_b64_e32 v[90:91], 0
	v_mov_b64_e32 v[100:101], 0
	v_mov_b64_e32 v[102:103], 0
	v_mov_b64_e32 v[104:105], 0
	v_mov_b64_e32 v[106:107], 0
	v_mov_b64_e32 v[116:117], 0
	v_mov_b64_e32 v[118:119], 0
	v_mov_b64_e32 v[120:121], 0
	v_mov_b64_e32 v[122:123], 0
	v_mov_b64_e32 v[76:77], 0
	v_mov_b64_e32 v[78:79], 0
	v_mov_b64_e32 v[80:81], 0
	v_mov_b64_e32 v[82:83], 0
	v_mov_b64_e32 v[92:93], 0
	v_mov_b64_e32 v[94:95], 0
	v_mov_b64_e32 v[96:97], 0
	v_mov_b64_e32 v[98:99], 0
	v_mov_b64_e32 v[108:109], 0
	v_mov_b64_e32 v[110:111], 0
	v_mov_b64_e32 v[112:113], 0
	v_mov_b64_e32 v[114:115], 0
	v_mov_b64_e32 v[124:125], 0
	v_mov_b64_e32 v[126:127], 0
	v_mov_b64_e32 v[128:129], 0
	v_mov_b64_e32 v[130:131], 0
	s_waitcnt vmcnt(0)

.LBB0_768:
	s_add_u32 s47, s22, 0x100
	v_mov_b32_e32 v4, 0
	s_addc_u32 s49, s23, 0
	s_mov_b32 s62, -2
	v_mov_b32_e32 v5, v4
	v_mov_b64_e32 v[6:7], 0
	v_mov_b64_e32 v[8:9], 0
	v_mov_b64_e32 v[10:11], 0
	v_mov_b64_e32 v[20:21], 0
	v_mov_b64_e32 v[22:23], 0
	v_mov_b64_e32 v[24:25], 0
	v_mov_b64_e32 v[26:27], 0
	v_mov_b64_e32 v[36:37], 0
	v_mov_b64_e32 v[38:39], 0
	v_mov_b64_e32 v[40:41], 0
	v_mov_b64_e32 v[42:43], 0
	v_mov_b64_e32 v[52:53], 0
	v_mov_b64_e32 v[54:55], 0
	v_mov_b64_e32 v[56:57], 0
	v_mov_b64_e32 v[58:59], 0
	v_mov_b64_e32 v[12:13], 0
	v_mov_b64_e32 v[14:15], 0
	v_mov_b64_e32 v[16:17], 0
	v_mov_b64_e32 v[18:19], 0
	v_mov_b64_e32 v[28:29], 0
	v_mov_b64_e32 v[30:31], 0
	v_mov_b64_e32 v[32:33], 0
	v_mov_b64_e32 v[34:35], 0
	v_mov_b64_e32 v[44:45], 0
	v_mov_b64_e32 v[46:47], 0
	v_mov_b64_e32 v[48:49], 0
	v_mov_b64_e32 v[50:51], 0
	v_mov_b64_e32 v[60:61], 0
	v_mov_b64_e32 v[62:63], 0
	v_mov_b64_e32 v[64:65], 0
	v_mov_b64_e32 v[66:67], 0
	v_mov_b64_e32 v[68:69], 0
	v_mov_b64_e32 v[70:71], 0
	v_mov_b64_e32 v[72:73], 0
	v_mov_b64_e32 v[74:75], 0
	v_mov_b64_e32 v[84:85], 0
	v_mov_b64_e32 v[86:87], 0
	v_mov_b64_e32 v[88:89], 0
	v_mov_b64_e32 v[90:91], 0
	v_mov_b64_e32 v[100:101], 0
	v_mov_b64_e32 v[102:103], 0
	v_mov_b64_e32 v[104:105], 0
	v_mov_b64_e32 v[106:107], 0
	v_mov_b64_e32 v[116:117], 0
	v_mov_b64_e32 v[118:119], 0
	v_mov_b64_e32 v[120:121], 0
	v_mov_b64_e32 v[122:123], 0
	v_mov_b64_e32 v[76:77], 0
	v_mov_b64_e32 v[78:79], 0
	v_mov_b64_e32 v[80:81], 0
	v_mov_b64_e32 v[82:83], 0
	v_mov_b64_e32 v[92:93], 0
	v_mov_b64_e32 v[94:95], 0
	v_mov_b64_e32 v[96:97], 0
	v_mov_b64_e32 v[98:99], 0
	v_mov_b64_e32 v[108:109], 0
	v_mov_b64_e32 v[110:111], 0
	v_mov_b64_e32 v[112:113], 0
	v_mov_b64_e32 v[114:115], 0
	v_mov_b64_e32 v[124:125], 0
	v_mov_b64_e32 v[126:127], 0
	v_mov_b64_e32 v[128:129], 0
	v_mov_b64_e32 v[130:131], 0

.LBB0_1011:
	s_ashr_i32 s29, s28, 31
	s_lshl_b64 s[34:35], s[28:29], 17
	s_add_u32 s34, s53, s34
	s_addc_u32 s35, s54, s35
	s_and_b64 s[16:17], s[16:17], exec
	v_mov_b32_e32 v4, 0
	s_cselect_b32 s9, s35, s1
	s_cselect_b32 s19, s34, s0
	s_mov_b64 s[36:37], 0
	s_mov_b64 s[16:17], -1
	s_mov_b64 s[38:39], 0
	v_mov_b32_e32 v5, v4
	v_mov_b64_e32 v[6:7], 0
	v_mov_b64_e32 v[8:9], 0
	v_mov_b64_e32 v[10:11], 0
	v_mov_b64_e32 v[20:21], 0
	v_mov_b64_e32 v[22:23], 0
	v_mov_b64_e32 v[24:25], 0
	v_mov_b64_e32 v[26:27], 0
	v_mov_b64_e32 v[36:37], 0
	v_mov_b64_e32 v[38:39], 0
	v_mov_b64_e32 v[40:41], 0
	v_mov_b64_e32 v[42:43], 0
	v_mov_b64_e32 v[52:53], 0
	v_mov_b64_e32 v[54:55], 0
	v_mov_b64_e32 v[56:57], 0
	v_mov_b64_e32 v[58:59], 0
	v_mov_b64_e32 v[12:13], 0
	v_mov_b64_e32 v[14:15], 0
	v_mov_b64_e32 v[16:17], 0
	v_mov_b64_e32 v[18:19], 0
	v_mov_b64_e32 v[28:29], 0
	v_mov_b64_e32 v[30:31], 0
	v_mov_b64_e32 v[32:33], 0
	v_mov_b64_e32 v[34:35], 0
	v_mov_b64_e32 v[44:45], 0
	v_mov_b64_e32 v[46:47], 0
	v_mov_b64_e32 v[48:49], 0
	v_mov_b64_e32 v[50:51], 0
	v_mov_b64_e32 v[60:61], 0
	v_mov_b64_e32 v[62:63], 0
	v_mov_b64_e32 v[64:65], 0
	v_mov_b64_e32 v[66:67], 0
	v_mov_b64_e32 v[72:73], 0
	v_mov_b64_e32 v[74:75], 0
	v_mov_b64_e32 v[76:77], 0
	v_mov_b64_e32 v[78:79], 0
	v_mov_b64_e32 v[92:93], 0
	v_mov_b64_e32 v[94:95], 0
	v_mov_b64_e32 v[96:97], 0
	v_mov_b64_e32 v[98:99], 0
	v_mov_b64_e32 v[112:113], 0
	v_mov_b64_e32 v[114:115], 0
	v_mov_b64_e32 v[116:117], 0
	v_mov_b64_e32 v[118:119], 0
	v_mov_b64_e32 v[132:133], 0
	v_mov_b64_e32 v[134:135], 0
	v_mov_b64_e32 v[136:137], 0
	v_mov_b64_e32 v[138:139], 0
	v_mov_b64_e32 v[80:81], 0
	v_mov_b64_e32 v[82:83], 0
	v_mov_b64_e32 v[84:85], 0
	v_mov_b64_e32 v[86:87], 0
	v_mov_b64_e32 v[100:101], 0
	v_mov_b64_e32 v[102:103], 0
	v_mov_b64_e32 v[104:105], 0
	v_mov_b64_e32 v[106:107], 0
	v_mov_b64_e32 v[120:121], 0
	v_mov_b64_e32 v[122:123], 0
	v_mov_b64_e32 v[124:125], 0
	v_mov_b64_e32 v[126:127], 0
	v_mov_b64_e32 v[140:141], 0
	v_mov_b64_e32 v[142:143], 0
	v_mov_b64_e32 v[144:145], 0
	v_mov_b64_e32 v[146:147], 0
	s_waitcnt vmcnt(0)

.LBB0_1764:
	s_ashr_i32 s41, s40, 31
	v_cmp_lt_i64_e32 vcc, s[14:15], v[202:203]
	s_lshl_b64 s[14:15], s[40:41], 19
	s_add_u32 s42, s52, s14
	s_addc_u32 s43, s53, s15
	s_and_b64 s[14:15], vcc, exec
	s_cselect_b32 s41, s43, s1
	s_cselect_b32 s65, s42, s0
	s_ashr_i32 s39, s38, 31
	s_lshl_b64 s[14:15], s[38:39], 19
	s_add_u32 s44, s54, s14
	s_addc_u32 s45, s55, s15
	s_and_b64 s[14:15], vcc, exec
	s_cselect_b32 s39, s45, s9
	s_cselect_b32 s67, s44, s8
	s_add_u32 s68, s8, 0x100
	v_mov_b32_e32 v4, 0
	s_addc_u32 s79, s9, 0
	s_mov_b32 s80, -2
	v_mov_b32_e32 v5, v4
	v_mov_b32_e32 v6, v4
	v_mov_b32_e32 v7, v4
	v_mov_b32_e32 v8, v4
	v_mov_b32_e32 v9, v4
	v_mov_b32_e32 v10, v4
	v_mov_b32_e32 v11, v4
	v_mov_b32_e32 v20, v4
	v_mov_b32_e32 v21, v4
	v_mov_b32_e32 v22, v4
	v_mov_b32_e32 v23, v4
	v_mov_b32_e32 v24, v4
	v_mov_b32_e32 v25, v4
	v_mov_b32_e32 v26, v4
	v_mov_b32_e32 v27, v4
	v_mov_b32_e32 v36, v4
	v_mov_b32_e32 v37, v4
	v_mov_b32_e32 v38, v4
	v_mov_b32_e32 v39, v4
	v_mov_b32_e32 v40, v4
	v_mov_b32_e32 v41, v4
	v_mov_b32_e32 v42, v4
	v_mov_b32_e32 v43, v4
	s_waitcnt vmcnt(0)
	v_mov_b64_e32 v[52:53], 0
	v_mov_b64_e32 v[54:55], 0
	v_mov_b64_e32 v[56:57], 0
	v_mov_b64_e32 v[58:59], 0
	v_mov_b64_e32 v[12:13], 0
	v_mov_b64_e32 v[14:15], 0
	v_mov_b64_e32 v[16:17], 0
	v_mov_b64_e32 v[18:19], 0
	v_mov_b64_e32 v[28:29], 0
	v_mov_b64_e32 v[30:31], 0
	v_mov_b64_e32 v[32:33], 0
	v_mov_b64_e32 v[34:35], 0
	v_mov_b64_e32 v[44:45], 0
	v_mov_b64_e32 v[46:47], 0
	v_mov_b64_e32 v[48:49], 0
	v_mov_b64_e32 v[50:51], 0
	v_mov_b64_e32 v[60:61], 0
	v_mov_b64_e32 v[62:63], 0
	v_mov_b64_e32 v[64:65], 0
	v_mov_b64_e32 v[66:67], 0
	v_mov_b64_e32 v[68:69], 0
	v_mov_b64_e32 v[70:71], 0
	v_mov_b64_e32 v[72:73], 0
	v_mov_b64_e32 v[74:75], 0
	v_mov_b64_e32 v[84:85], 0
	v_mov_b64_e32 v[86:87], 0
	v_mov_b64_e32 v[88:89], 0
	v_mov_b64_e32 v[90:91], 0
	v_mov_b64_e32 v[100:101], 0
	v_mov_b64_e32 v[102:103], 0
	v_mov_b64_e32 v[104:105], 0
	v_mov_b64_e32 v[106:107], 0
	v_mov_b64_e32 v[116:117], 0
	v_mov_b64_e32 v[118:119], 0
	v_mov_b64_e32 v[120:121], 0
	v_mov_b64_e32 v[122:123], 0
	v_mov_b64_e32 v[76:77], 0
	v_mov_b64_e32 v[78:79], 0
	v_mov_b64_e32 v[80:81], 0
	v_mov_b64_e32 v[82:83], 0
	v_mov_b64_e32 v[92:93], 0
	v_mov_b64_e32 v[94:95], 0
	v_mov_b64_e32 v[96:97], 0
	v_mov_b64_e32 v[98:99], 0
	v_mov_b64_e32 v[108:109], 0
	v_mov_b64_e32 v[110:111], 0
	v_mov_b64_e32 v[112:113], 0
	v_mov_b64_e32 v[114:115], 0
	v_mov_b64_e32 v[124:125], 0
	v_mov_b64_e32 v[126:127], 0
	v_mov_b64_e32 v[128:129], 0
	v_mov_b64_e32 v[130:131], 0

.LBB0_1911:
	v_and_b32_e32 v3, 15, v1
	v_and_b32_e32 v4, 48, v1
	v_lshlrev_b32_e32 v3, 6, v3
	v_lshlrev_b32_e32 v1, 2, v1
	v_or_b32_e32 v5, v3, v4
	v_and_b32_e32 v1, 32, v1
	s_lshl_b32 s17, s17, 12
	s_lshl_b32 s16, s16, 13
	v_bitop3_b32 v3, v3, v1, v4 bitop3:0x36
	v_bitop3_b32 v6, v5, s16, v1 bitop3:0xde
	s_and_b32 s16, s17, 0x3000
	v_or_b32_e32 v1, s16, v3
	s_add_u32 s16, s14, 0x80
	v_mov_b32_e32 v133, v2
	s_addc_u32 s17, s15, 0
	s_waitcnt vmcnt(4)
	s_barrier
	s_add_i32 m0, s42, 0x18000
	v_lshl_add_u64 v[4:5], s[16:17], 0, v[132:133]
	v_mov_b32_e32 v135, v2
	global_load_lds_dwordx4 v[4:5], off
	s_add_i32 m0, s42, 0x1a000
	v_lshl_add_u64 v[4:5], s[16:17], 0, v[134:135]
	s_add_u32 s16, s24, 0x7bfdc80
	s_addc_u32 s17, s25, 0
	s_add_i32 s46, s42, 0x8000
	global_load_lds_dwordx4 v[4:5], off
	s_mov_b32 m0, s46
	v_lshl_add_u64 v[4:5], s[16:17], 0, v[132:133]
	s_add_i32 s47, s42, 0xa000
	global_load_lds_dwordx4 v[4:5], off
	v_lshl_add_u64 v[4:5], s[16:17], 0, v[134:135]
	s_add_u32 s16, s14, 0x40080
	s_mov_b32 m0, s47
	s_addc_u32 s17, s15, 0
	global_load_lds_dwordx4 v[4:5], off
	s_add_i32 m0, s42, 0x1c000
	v_lshl_add_u64 v[4:5], s[16:17], 0, v[132:133]
	global_load_lds_dwordx4 v[4:5], off
	v_lshl_add_u64 v[4:5], s[16:17], 0, v[134:135]
	s_add_i32 m0, s42, 0x1e000
	s_mov_b32 s51, -2
	global_load_lds_dwordx4 v[4:5], off
	s_waitcnt vmcnt(6)
	v_mov_b32_e32 v4, 0
	v_add_u32_e32 v3, 0, v6
	s_mov_b64 s[16:17], s[24:25]
	v_mov_b32_e32 v5, v4
	v_mov_b32_e32 v6, v4
	v_mov_b32_e32 v7, v4
	v_mov_b32_e32 v8, v4
	v_mov_b32_e32 v9, v4
	v_mov_b32_e32 v10, v4
	v_mov_b32_e32 v11, v4
	v_mov_b32_e32 v20, v4
	v_mov_b32_e32 v21, v4
	v_mov_b32_e32 v22, v4
	v_mov_b32_e32 v23, v4
	v_mov_b32_e32 v24, v4
	v_mov_b32_e32 v25, v4
	v_mov_b32_e32 v26, v4
	v_mov_b32_e32 v27, v4
	v_mov_b32_e32 v36, v4
	v_mov_b32_e32 v37, v4
	v_mov_b32_e32 v38, v4
	v_mov_b32_e32 v39, v4
	v_mov_b32_e32 v40, v4
	v_mov_b32_e32 v41, v4
	v_mov_b32_e32 v42, v4
	v_mov_b32_e32 v43, v4
	s_waitcnt vmcnt(0)
	v_mov_b64_e32 v[52:53], 0
	v_mov_b64_e32 v[54:55], 0
	v_mov_b64_e32 v[56:57], 0
	v_mov_b64_e32 v[58:59], 0
	v_mov_b64_e32 v[12:13], 0
	v_mov_b64_e32 v[14:15], 0
	v_mov_b64_e32 v[16:17], 0
	v_mov_b64_e32 v[18:19], 0
	v_mov_b64_e32 v[28:29], 0
	v_mov_b64_e32 v[30:31], 0
	v_mov_b64_e32 v[32:33], 0
	v_mov_b64_e32 v[34:35], 0
	v_mov_b64_e32 v[44:45], 0
	v_mov_b64_e32 v[46:47], 0
	v_mov_b64_e32 v[48:49], 0
	v_mov_b64_e32 v[50:51], 0
	v_mov_b64_e32 v[60:61], 0
	v_mov_b64_e32 v[62:63], 0
	v_mov_b64_e32 v[64:65], 0
	v_mov_b64_e32 v[66:67], 0
	v_mov_b64_e32 v[68:69], 0
	v_mov_b64_e32 v[70:71], 0
	v_mov_b64_e32 v[72:73], 0
	v_mov_b64_e32 v[74:75], 0
	v_mov_b64_e32 v[84:85], 0
	v_mov_b64_e32 v[86:87], 0
	v_mov_b64_e32 v[88:89], 0
	v_mov_b64_e32 v[90:91], 0
	v_mov_b64_e32 v[100:101], 0
	v_mov_b64_e32 v[102:103], 0
	v_mov_b64_e32 v[104:105], 0
	v_mov_b64_e32 v[106:107], 0
	v_mov_b64_e32 v[116:117], 0
	v_mov_b64_e32 v[118:119], 0
	v_mov_b64_e32 v[120:121], 0
	v_mov_b64_e32 v[122:123], 0
	v_mov_b64_e32 v[76:77], 0
	v_mov_b64_e32 v[78:79], 0
	v_mov_b64_e32 v[80:81], 0
	v_mov_b64_e32 v[82:83], 0
	v_mov_b64_e32 v[92:93], 0
	v_mov_b64_e32 v[94:95], 0
	v_mov_b64_e32 v[96:97], 0
	v_mov_b64_e32 v[98:99], 0
	v_mov_b64_e32 v[108:109], 0
	v_mov_b64_e32 v[110:111], 0
	v_mov_b64_e32 v[112:113], 0
	v_mov_b64_e32 v[114:115], 0
	v_mov_b64_e32 v[124:125], 0
	v_mov_b64_e32 v[126:127], 0
	v_mov_b64_e32 v[128:129], 0
	v_mov_b64_e32 v[130:131], 0
	v_readlane_b32 s56, v255, 22
	v_readlane_b32 s57, v255, 21
	s_barrier

.LBB0_2212:
	s_ashr_i32 s7, s6, 31
	s_lshl_b64 s[18:19], s[6:7], 17
	s_add_u32 s18, s49, s18
	s_addc_u32 s19, s50, s19
	s_and_b64 s[22:23], s[22:23], exec
	v_mov_b32_e32 v4, 0
	s_cselect_b32 s1, s19, s17
	s_cselect_b32 s7, s18, s16
	s_mov_b64 s[24:25], 0
	s_mov_b64 s[22:23], -1
	s_mov_b64 s[26:27], 0
	s_waitcnt lgkmcnt(0)
	v_mov_b32_e32 v5, v4
	v_mov_b32_e32 v6, v4
	v_mov_b32_e32 v7, v4
	v_mov_b32_e32 v8, v4
	v_mov_b32_e32 v9, v4
	v_mov_b32_e32 v10, v4
	v_mov_b32_e32 v11, v4
	v_mov_b32_e32 v20, v4
	v_mov_b32_e32 v21, v4
	v_mov_b32_e32 v22, v4
	v_mov_b32_e32 v23, v4
	v_mov_b32_e32 v24, v4
	v_mov_b32_e32 v25, v4
	v_mov_b32_e32 v26, v4
	v_mov_b32_e32 v27, v4
	v_mov_b32_e32 v36, v4
	v_mov_b32_e32 v37, v4
	v_mov_b32_e32 v38, v4
	v_mov_b32_e32 v39, v4
	v_mov_b32_e32 v40, v4
	v_mov_b32_e32 v41, v4
	v_mov_b32_e32 v42, v4
	v_mov_b32_e32 v43, v4
	s_waitcnt vmcnt(0)
	v_mov_b64_e32 v[52:53], 0
	v_mov_b64_e32 v[54:55], 0
	v_mov_b64_e32 v[56:57], 0
	v_mov_b64_e32 v[58:59], 0
	v_mov_b64_e32 v[12:13], 0
	v_mov_b64_e32 v[14:15], 0
	v_mov_b64_e32 v[16:17], 0
	v_mov_b64_e32 v[18:19], 0
	v_mov_b64_e32 v[28:29], 0
	v_mov_b64_e32 v[30:31], 0
	v_mov_b64_e32 v[32:33], 0
	v_mov_b64_e32 v[34:35], 0
	v_mov_b64_e32 v[44:45], 0
	v_mov_b64_e32 v[46:47], 0
	v_mov_b64_e32 v[48:49], 0
	v_mov_b64_e32 v[50:51], 0
	v_mov_b64_e32 v[60:61], 0
	v_mov_b64_e32 v[62:63], 0
	v_mov_b64_e32 v[64:65], 0
	v_mov_b64_e32 v[66:67], 0
	v_mov_b64_e32 v[68:69], 0
	v_mov_b64_e32 v[70:71], 0
	v_mov_b64_e32 v[72:73], 0
	v_mov_b64_e32 v[74:75], 0
	v_mov_b64_e32 v[84:85], 0
	v_mov_b64_e32 v[86:87], 0
	v_mov_b64_e32 v[88:89], 0
	v_mov_b64_e32 v[90:91], 0
	v_mov_b64_e32 v[100:101], 0
	v_mov_b64_e32 v[102:103], 0
	v_mov_b64_e32 v[104:105], 0
	v_mov_b64_e32 v[106:107], 0
	v_mov_b64_e32 v[116:117], 0
	v_mov_b64_e32 v[118:119], 0
	v_mov_b64_e32 v[120:121], 0
	v_mov_b64_e32 v[122:123], 0
	v_mov_b64_e32 v[76:77], 0
	v_mov_b64_e32 v[78:79], 0
	v_mov_b64_e32 v[80:81], 0
	v_mov_b64_e32 v[82:83], 0
	v_mov_b64_e32 v[92:93], 0
	v_mov_b64_e32 v[94:95], 0
	v_mov_b64_e32 v[96:97], 0
	v_mov_b64_e32 v[98:99], 0
	v_mov_b64_e32 v[108:109], 0
	v_mov_b64_e32 v[110:111], 0
	v_mov_b64_e32 v[112:113], 0
	v_mov_b64_e32 v[114:115], 0
	v_mov_b64_e32 v[124:125], 0
	v_mov_b64_e32 v[126:127], 0
	v_mov_b64_e32 v[128:129], 0
	v_mov_b64_e32 v[130:131], 0

.LBB0_2602:
	s_add_u32 s47, s22, 0x100
	v_mov_b32_e32 v4, 0
	s_addc_u32 s48, s23, 0
	s_mov_b32 s49, -2
	v_mov_b32_e32 v5, v4
	v_mov_b64_e32 v[6:7], 0
	v_mov_b64_e32 v[8:9], 0
	v_mov_b64_e32 v[10:11], 0
	v_mov_b64_e32 v[12:13], 0
	v_mov_b64_e32 v[14:15], 0
	v_mov_b64_e32 v[16:17], 0
	v_mov_b64_e32 v[18:19], 0
	v_mov_b64_e32 v[28:29], 0
	v_mov_b64_e32 v[30:31], 0
	v_mov_b64_e32 v[32:33], 0
	v_mov_b64_e32 v[34:35], 0
	v_mov_b64_e32 v[44:45], 0
	v_mov_b64_e32 v[46:47], 0
	v_mov_b64_e32 v[48:49], 0
	v_mov_b64_e32 v[50:51], 0
	v_mov_b64_e32 v[20:21], 0
	v_mov_b64_e32 v[22:23], 0
	v_mov_b64_e32 v[24:25], 0
	v_mov_b64_e32 v[26:27], 0
	v_mov_b64_e32 v[36:37], 0
	v_mov_b64_e32 v[38:39], 0
	v_mov_b64_e32 v[40:41], 0
	v_mov_b64_e32 v[42:43], 0
	v_mov_b64_e32 v[52:53], 0
	v_mov_b64_e32 v[54:55], 0
	v_mov_b64_e32 v[56:57], 0
	v_mov_b64_e32 v[58:59], 0
	v_mov_b64_e32 v[60:61], 0
	v_mov_b64_e32 v[62:63], 0
	v_mov_b64_e32 v[64:65], 0
	v_mov_b64_e32 v[66:67], 0
	v_mov_b64_e32 v[68:69], 0
	v_mov_b64_e32 v[70:71], 0
	v_mov_b64_e32 v[72:73], 0
	v_mov_b64_e32 v[74:75], 0
	v_mov_b64_e32 v[76:77], 0
	v_mov_b64_e32 v[78:79], 0
	v_mov_b64_e32 v[84:85], 0
	v_mov_b64_e32 v[86:87], 0
	v_mov_b64_e32 v[92:93], 0
	v_mov_b64_e32 v[94:95], 0
	v_mov_b64_e32 v[100:101], 0
	v_mov_b64_e32 v[102:103], 0
	v_mov_b64_e32 v[108:109], 0
	v_mov_b64_e32 v[110:111], 0
	v_mov_b64_e32 v[116:117], 0
	v_mov_b64_e32 v[118:119], 0
	v_mov_b64_e32 v[80:81], 0
	v_mov_b64_e32 v[82:83], 0
	v_mov_b64_e32 v[88:89], 0
	v_mov_b64_e32 v[90:91], 0
	v_mov_b64_e32 v[96:97], 0
	v_mov_b64_e32 v[98:99], 0
	v_mov_b64_e32 v[104:105], 0
	v_mov_b64_e32 v[106:107], 0
	v_mov_b64_e32 v[112:113], 0
	v_mov_b64_e32 v[114:115], 0
	v_mov_b64_e32 v[120:121], 0
	v_mov_b64_e32 v[122:123], 0
	v_mov_b64_e32 v[124:125], 0
	v_mov_b64_e32 v[126:127], 0
	v_mov_b64_e32 v[128:129], 0
	v_mov_b64_e32 v[130:131], 0

.LBB0_2673:
	s_ashr_i32 s31, s30, 31
	s_lshl_b64 s[14:15], s[30:31], 19
	s_add_u32 s36, s45, s14
	s_addc_u32 s37, s46, s15
	s_and_b64 s[14:15], s[16:17], exec
	s_cselect_b32 s31, s37, s1
	s_cselect_b32 s68, s36, s0
	s_ashr_i32 s29, s28, 31
	s_lshl_b64 s[14:15], s[28:29], 19
	s_add_u32 s38, s47, s14
	s_addc_u32 s39, s48, s15
	s_and_b64 s[14:15], s[16:17], exec
	s_cselect_b32 s29, s39, s9
	s_cselect_b32 s72, s38, s8
	s_add_u32 s73, s8, 0x100
	v_mov_b32_e32 v4, 0
	s_addc_u32 s74, s9, 0
	s_mov_b32 s75, -2
	s_waitcnt lgkmcnt(0)
	v_mov_b32_e32 v5, v4
	v_mov_b32_e32 v6, v4
	v_mov_b32_e32 v7, v4
	v_mov_b32_e32 v8, v4
	v_mov_b32_e32 v9, v4
	s_waitcnt vmcnt(0)
	v_mov_b64_e32 v[10:11], 0
	v_mov_b64_e32 v[20:21], 0
	v_mov_b64_e32 v[22:23], 0
	v_mov_b64_e32 v[24:25], 0
	v_mov_b64_e32 v[26:27], 0
	v_mov_b64_e32 v[36:37], 0
	v_mov_b64_e32 v[38:39], 0
	v_mov_b64_e32 v[40:41], 0
	v_mov_b64_e32 v[42:43], 0
	v_mov_b64_e32 v[44:45], 0
	v_mov_b64_e32 v[46:47], 0
	v_mov_b64_e32 v[48:49], 0
	v_mov_b64_e32 v[50:51], 0
	v_mov_b64_e32 v[12:13], 0
	v_mov_b64_e32 v[14:15], 0
	v_mov_b64_e32 v[16:17], 0
	v_mov_b64_e32 v[18:19], 0
	v_mov_b64_e32 v[28:29], 0
	v_mov_b64_e32 v[30:31], 0
	v_mov_b64_e32 v[32:33], 0
	v_mov_b64_e32 v[34:35], 0
	v_mov_b64_e32 v[52:53], 0
	v_mov_b64_e32 v[54:55], 0
	v_mov_b64_e32 v[56:57], 0
	v_mov_b64_e32 v[58:59], 0
	v_mov_b64_e32 v[60:61], 0
	v_mov_b64_e32 v[62:63], 0
	v_mov_b64_e32 v[64:65], 0
	v_mov_b64_e32 v[66:67], 0
	v_mov_b64_e32 v[68:69], 0
	v_mov_b64_e32 v[70:71], 0
	v_mov_b64_e32 v[72:73], 0
	v_mov_b64_e32 v[74:75], 0
	v_mov_b64_e32 v[84:85], 0
	v_mov_b64_e32 v[86:87], 0
	v_mov_b64_e32 v[88:89], 0
	v_mov_b64_e32 v[90:91], 0
	v_mov_b64_e32 v[100:101], 0
	v_mov_b64_e32 v[102:103], 0
	v_mov_b64_e32 v[104:105], 0
	v_mov_b64_e32 v[106:107], 0
	v_mov_b64_e32 v[116:117], 0
	v_mov_b64_e32 v[118:119], 0
	v_mov_b64_e32 v[120:121], 0
	v_mov_b64_e32 v[122:123], 0
	v_mov_b64_e32 v[76:77], 0
	v_mov_b64_e32 v[78:79], 0
	v_mov_b64_e32 v[80:81], 0
	v_mov_b64_e32 v[82:83], 0
	v_mov_b64_e32 v[92:93], 0
	v_mov_b64_e32 v[94:95], 0
	v_mov_b64_e32 v[96:97], 0
	v_mov_b64_e32 v[98:99], 0
	v_mov_b64_e32 v[108:109], 0
	v_mov_b64_e32 v[110:111], 0
	v_mov_b64_e32 v[112:113], 0
	v_mov_b64_e32 v[114:115], 0
	v_mov_b64_e32 v[124:125], 0
	v_mov_b64_e32 v[126:127], 0
	v_mov_b64_e32 v[128:129], 0
	v_mov_b64_e32 v[130:131], 0

.LBB0_2740:
	v_and_b32_e32 v3, 15, v1
	v_and_b32_e32 v4, 48, v1
	v_lshlrev_b32_e32 v3, 6, v3
	v_lshlrev_b32_e32 v1, 2, v1
	v_or_b32_e32 v5, v3, v4
	v_and_b32_e32 v1, 32, v1
	s_lshl_b32 s21, s21, 12
	s_lshl_b32 s20, s20, 13
	v_bitop3_b32 v3, v3, v1, v4 bitop3:0x36
	v_bitop3_b32 v6, v5, s20, v1 bitop3:0xde
	s_and_b32 s20, s21, 0x3000
	v_or_b32_e32 v1, s20, v3
	s_add_u32 s20, s14, 0x80
	v_mov_b32_e32 v135, v2
	s_addc_u32 s21, s15, 0
	s_waitcnt vmcnt(4)
	s_barrier
	s_add_i32 m0, s42, 0x18000
	v_lshl_add_u64 v[4:5], s[20:21], 0, v[134:135]
	v_mov_b32_e32 v139, v2
	global_load_lds_dwordx4 v[4:5], off
	s_add_i32 m0, s42, 0x1a000
	v_lshl_add_u64 v[4:5], s[20:21], 0, v[138:139]
	s_add_u32 s20, s0, 0x80
	v_mov_b32_e32 v133, v2
	s_addc_u32 s21, s1, 0
	s_add_i32 s47, s42, 0x8000
	v_mov_b32_e32 v137, v2
	global_load_lds_dwordx4 v[4:5], off
	s_mov_b32 m0, s47
	v_lshl_add_u64 v[4:5], s[20:21], 0, v[132:133]
	s_add_i32 s50, s42, 0xa000
	global_load_lds_dwordx4 v[4:5], off
	v_lshl_add_u64 v[4:5], s[20:21], 0, v[136:137]
	s_add_u32 s20, s14, 0x18080
	s_mov_b32 m0, s50
	s_addc_u32 s21, s15, 0
	global_load_lds_dwordx4 v[4:5], off
	s_add_i32 m0, s42, 0x1c000
	v_lshl_add_u64 v[4:5], s[20:21], 0, v[134:135]
	global_load_lds_dwordx4 v[4:5], off
	v_lshl_add_u64 v[4:5], s[20:21], 0, v[138:139]
	s_add_i32 m0, s42, 0x1e000
	v_readlane_b32 s20, v255, 11
	global_load_lds_dwordx4 v[4:5], off
	s_add_u32 s20, s38, s20
	v_readlane_b32 s21, v255, 12
	s_waitcnt vmcnt(6)
	s_addc_u32 s21, s39, s21
	s_add_u32 s51, s20, s19
	v_mov_b32_e32 v4, 0
	s_addc_u32 s64, s21, s18
	s_mov_b32 s65, -2
	v_add_u32_e32 v3, 0, v6
	s_mov_b64 s[18:19], s[0:1]
	v_mov_b32_e32 v5, v4
	v_mov_b32_e32 v6, v4
	v_mov_b32_e32 v7, v4
	v_mov_b32_e32 v8, v4
	v_mov_b32_e32 v9, v4
	v_mov_b32_e32 v10, v4
	v_mov_b32_e32 v11, v4
	v_mov_b32_e32 v12, v4
	v_mov_b32_e32 v13, v4
	s_waitcnt vmcnt(0)
	v_mov_b64_e32 v[14:15], 0
	v_mov_b64_e32 v[16:17], 0
	v_mov_b64_e32 v[18:19], 0
	v_mov_b64_e32 v[28:29], 0
	v_mov_b64_e32 v[30:31], 0
	v_mov_b64_e32 v[32:33], 0
	v_mov_b64_e32 v[34:35], 0
	v_mov_b64_e32 v[44:45], 0
	v_mov_b64_e32 v[46:47], 0
	v_mov_b64_e32 v[48:49], 0
	v_mov_b64_e32 v[50:51], 0
	v_mov_b64_e32 v[20:21], 0
	v_mov_b64_e32 v[22:23], 0
	v_mov_b64_e32 v[24:25], 0
	v_mov_b64_e32 v[26:27], 0
	v_mov_b64_e32 v[36:37], 0
	v_mov_b64_e32 v[38:39], 0
	v_mov_b64_e32 v[40:41], 0
	v_mov_b64_e32 v[42:43], 0
	v_mov_b64_e32 v[52:53], 0
	v_mov_b64_e32 v[54:55], 0
	v_mov_b64_e32 v[56:57], 0
	v_mov_b64_e32 v[58:59], 0
	v_mov_b64_e32 v[60:61], 0
	v_mov_b64_e32 v[62:63], 0
	v_mov_b64_e32 v[64:65], 0
	v_mov_b64_e32 v[66:67], 0
	v_mov_b64_e32 v[68:69], 0
	v_mov_b64_e32 v[70:71], 0
	v_mov_b64_e32 v[72:73], 0
	v_mov_b64_e32 v[74:75], 0
	v_mov_b64_e32 v[76:77], 0
	v_mov_b64_e32 v[78:79], 0
	v_mov_b64_e32 v[80:81], 0
	v_mov_b64_e32 v[82:83], 0
	v_mov_b64_e32 v[92:93], 0
	v_mov_b64_e32 v[94:95], 0
	v_mov_b64_e32 v[96:97], 0
	v_mov_b64_e32 v[98:99], 0
	v_mov_b64_e32 v[108:109], 0
	v_mov_b64_e32 v[110:111], 0
	v_mov_b64_e32 v[112:113], 0
	v_mov_b64_e32 v[114:115], 0
	v_mov_b64_e32 v[84:85], 0
	v_mov_b64_e32 v[86:87], 0
	v_mov_b64_e32 v[88:89], 0
	v_mov_b64_e32 v[90:91], 0
	v_mov_b64_e32 v[100:101], 0
	v_mov_b64_e32 v[102:103], 0
	v_mov_b64_e32 v[104:105], 0
	v_mov_b64_e32 v[106:107], 0
	v_mov_b64_e32 v[116:117], 0
	v_mov_b64_e32 v[118:119], 0
	v_mov_b64_e32 v[120:121], 0
	v_mov_b64_e32 v[122:123], 0
	v_mov_b64_e32 v[124:125], 0
	v_mov_b64_e32 v[126:127], 0
	v_mov_b64_e32 v[128:129], 0
	v_mov_b64_e32 v[130:131], 0
	s_barrier

.LBB0_2765:
	v_and_b32_e32 v3, 15, v1
	v_and_b32_e32 v4, 48, v1
	v_lshlrev_b32_e32 v3, 6, v3
	v_lshlrev_b32_e32 v1, 2, v1
	v_or_b32_e32 v5, v3, v4
	v_and_b32_e32 v1, 32, v1
	s_lshl_b32 s15, s15, 12
	s_lshl_b32 s14, s14, 13
	v_bitop3_b32 v3, v3, v1, v4 bitop3:0x36
	v_bitop3_b32 v6, v5, s14, v1 bitop3:0xde
	s_and_b32 s14, s15, 0x3000
	v_or_b32_e32 v1, s14, v3
	s_add_u32 s14, s8, 0x80
	v_mov_b32_e32 v133, v2
	s_addc_u32 s15, s9, 0
	s_waitcnt vmcnt(2)
	s_barrier
	s_add_i32 m0, s42, 0x18000
	v_lshl_add_u64 v[4:5], s[14:15], 0, v[132:133]
	v_mov_b32_e32 v135, v2
	global_load_lds_dwordx4 v[4:5], off
	s_add_i32 m0, s42, 0x1a000
	v_lshl_add_u64 v[4:5], s[14:15], 0, v[134:135]
	s_add_u32 s14, s38, 0xd55ec80
	s_addc_u32 s15, s39, 0
	s_add_i32 s46, s42, 0x8000
	global_load_lds_dwordx4 v[4:5], off
	s_mov_b32 m0, s46
	v_lshl_add_u64 v[4:5], s[14:15], 0, v[132:133]
	s_add_i32 s47, s42, 0xa000
	global_load_lds_dwordx4 v[4:5], off
	v_lshl_add_u64 v[4:5], s[14:15], 0, v[134:135]
	s_add_u32 s14, s8, 0x40080
	s_mov_b32 m0, s47
	s_addc_u32 s15, s9, 0
	global_load_lds_dwordx4 v[4:5], off
	s_add_i32 m0, s42, 0x1c000
	v_lshl_add_u64 v[4:5], s[14:15], 0, v[132:133]
	global_load_lds_dwordx4 v[4:5], off
	v_lshl_add_u64 v[4:5], s[14:15], 0, v[134:135]
	s_add_i32 m0, s42, 0x1e000
	v_readlane_b32 s14, v254, 10
	global_load_lds_dwordx4 v[4:5], off
	s_waitcnt vmcnt(6)
	v_readlane_b32 s15, v254, 11
	s_add_u32 s50, s14, s34
	v_mov_b32_e32 v4, 0
	s_addc_u32 s51, s15, s35
	s_mov_b32 s56, -2
	v_add_u32_e32 v3, 0, v6
	s_mov_b64 s[14:15], s[0:1]
	v_mov_b32_e32 v5, v4
	v_mov_b64_e32 v[6:7], 0
	v_mov_b64_e32 v[8:9], 0
	v_mov_b64_e32 v[10:11], 0
	v_mov_b64_e32 v[20:21], 0
	v_mov_b64_e32 v[22:23], 0
	v_mov_b64_e32 v[24:25], 0
	v_mov_b64_e32 v[26:27], 0
	v_mov_b64_e32 v[36:37], 0
	v_mov_b64_e32 v[38:39], 0
	v_mov_b64_e32 v[40:41], 0
	v_mov_b64_e32 v[42:43], 0
	v_mov_b64_e32 v[52:53], 0
	v_mov_b64_e32 v[54:55], 0
	v_mov_b64_e32 v[56:57], 0
	v_mov_b64_e32 v[58:59], 0
	v_mov_b64_e32 v[12:13], 0
	v_mov_b64_e32 v[14:15], 0
	v_mov_b64_e32 v[16:17], 0
	v_mov_b64_e32 v[18:19], 0
	v_mov_b64_e32 v[28:29], 0
	v_mov_b64_e32 v[30:31], 0
	v_mov_b64_e32 v[32:33], 0
	v_mov_b64_e32 v[34:35], 0
	v_mov_b64_e32 v[44:45], 0
	v_mov_b64_e32 v[46:47], 0
	v_mov_b64_e32 v[48:49], 0
	v_mov_b64_e32 v[50:51], 0
	v_mov_b64_e32 v[60:61], 0
	v_mov_b64_e32 v[62:63], 0
	v_mov_b64_e32 v[64:65], 0
	v_mov_b64_e32 v[66:67], 0
	v_mov_b64_e32 v[68:69], 0
	v_mov_b64_e32 v[70:71], 0
	v_mov_b64_e32 v[72:73], 0
	v_mov_b64_e32 v[74:75], 0
	v_mov_b64_e32 v[84:85], 0
	v_mov_b64_e32 v[86:87], 0
	v_mov_b64_e32 v[88:89], 0
	v_mov_b64_e32 v[90:91], 0
	v_mov_b64_e32 v[100:101], 0
	v_mov_b64_e32 v[102:103], 0
	v_mov_b64_e32 v[104:105], 0
	v_mov_b64_e32 v[106:107], 0
	v_mov_b64_e32 v[116:117], 0
	v_mov_b64_e32 v[118:119], 0
	v_mov_b64_e32 v[120:121], 0
	v_mov_b64_e32 v[122:123], 0
	v_mov_b64_e32 v[76:77], 0
	v_mov_b64_e32 v[78:79], 0
	v_mov_b64_e32 v[80:81], 0
	v_mov_b64_e32 v[82:83], 0
	v_mov_b64_e32 v[92:93], 0
	v_mov_b64_e32 v[94:95], 0
	v_mov_b64_e32 v[96:97], 0
	v_mov_b64_e32 v[98:99], 0
	v_mov_b64_e32 v[108:109], 0
	v_mov_b64_e32 v[110:111], 0
	v_mov_b64_e32 v[112:113], 0
	v_mov_b64_e32 v[114:115], 0
	v_mov_b64_e32 v[124:125], 0
	v_mov_b64_e32 v[126:127], 0
	v_mov_b64_e32 v[128:129], 0
	v_mov_b64_e32 v[130:131], 0
	s_barrier

.LBB0_2832:
	s_ashr_i32 s75, s74, 31
	s_xor_b64 s[86:87], s[0:1], -1
	s_lshl_b64 s[14:15], s[74:75], 19
	s_add_u32 s80, s34, s14
	s_addc_u32 s81, s35, s15
	s_and_b64 s[14:15], s[0:1], exec
	s_cselect_b32 s64, s9, s81
	s_cselect_b32 s65, s8, s80
	s_ashr_i32 s63, s62, 31
	s_lshl_b64 s[14:15], s[62:63], 19
	s_add_u32 s82, s46, s14
	s_addc_u32 s83, s47, s15
	s_and_b64 s[14:15], s[0:1], exec
	s_cselect_b32 s63, s17, s83
	s_cselect_b32 s67, s16, s82
	v_mov_b32_e32 v4, 0
	s_cmp_lg_u32 s74, 64
	s_mov_b32 s75, 0
	s_cselect_b64 s[14:15], -1, 0
	v_mov_b32_e32 v5, v4
	v_mov_b64_e32 v[6:7], 0
	v_mov_b64_e32 v[12:13], 0
	v_mov_b64_e32 v[14:15], 0
	v_mov_b64_e32 v[20:21], 0
	v_mov_b64_e32 v[22:23], 0
	v_mov_b64_e32 v[28:29], 0
	v_mov_b64_e32 v[30:31], 0
	v_mov_b64_e32 v[36:37], 0
	v_mov_b64_e32 v[38:39], 0
	v_mov_b64_e32 v[44:45], 0
	v_mov_b64_e32 v[46:47], 0
	v_mov_b64_e32 v[52:53], 0
	v_mov_b64_e32 v[54:55], 0
	v_mov_b64_e32 v[60:61], 0
	v_mov_b64_e32 v[62:63], 0
	v_mov_b64_e32 v[8:9], 0
	v_mov_b64_e32 v[10:11], 0
	v_mov_b64_e32 v[16:17], 0
	v_mov_b64_e32 v[18:19], 0
	v_mov_b64_e32 v[24:25], 0
	v_mov_b64_e32 v[26:27], 0
	v_mov_b64_e32 v[32:33], 0
	v_mov_b64_e32 v[34:35], 0
	v_mov_b64_e32 v[40:41], 0
	v_mov_b64_e32 v[42:43], 0
	v_mov_b64_e32 v[48:49], 0
	v_mov_b64_e32 v[50:51], 0
	v_mov_b64_e32 v[56:57], 0
	v_mov_b64_e32 v[58:59], 0
	v_mov_b64_e32 v[64:65], 0
	v_mov_b64_e32 v[66:67], 0
	v_mov_b64_e32 v[68:69], 0
	v_mov_b64_e32 v[70:71], 0
	v_mov_b64_e32 v[76:77], 0
	v_mov_b64_e32 v[78:79], 0
	v_mov_b64_e32 v[84:85], 0
	v_mov_b64_e32 v[86:87], 0
	v_mov_b64_e32 v[92:93], 0
	v_mov_b64_e32 v[94:95], 0
	v_mov_b64_e32 v[100:101], 0
	v_mov_b64_e32 v[102:103], 0
	v_mov_b64_e32 v[108:109], 0
	v_mov_b64_e32 v[110:111], 0
	v_mov_b64_e32 v[116:117], 0
	v_mov_b64_e32 v[118:119], 0
	v_mov_b64_e32 v[120:121], 0
	v_mov_b64_e32 v[122:123], 0
	v_mov_b64_e32 v[72:73], 0
	v_mov_b64_e32 v[74:75], 0
	v_mov_b64_e32 v[80:81], 0
	v_mov_b64_e32 v[82:83], 0
	v_mov_b64_e32 v[88:89], 0
	v_mov_b64_e32 v[90:91], 0
	v_mov_b64_e32 v[96:97], 0
	v_mov_b64_e32 v[98:99], 0
	v_mov_b64_e32 v[104:105], 0
	v_mov_b64_e32 v[106:107], 0
	v_mov_b64_e32 v[112:113], 0
	v_mov_b64_e32 v[114:115], 0
	v_mov_b64_e32 v[124:125], 0
	v_mov_b64_e32 v[126:127], 0
	v_mov_b64_e32 v[128:129], 0
	v_mov_b64_e32 v[130:131], 0
	s_branch .LBB0_2837

.LBB0_3049:
	s_ashr_i32 s9, s8, 31
	s_lshl_b64 s[16:17], s[8:9], 17
	s_add_u32 s20, s54, s16
	s_addc_u32 s21, s55, s17
	s_and_b64 s[16:17], s[24:25], exec
	v_mov_b32_e32 v4, 0
	s_cselect_b32 s1, s21, s15
	s_cselect_b32 s9, s20, s14
	s_mov_b64 s[24:25], 0
	s_mov_b64 s[16:17], -1
	s_mov_b64 s[26:27], 0
	s_waitcnt lgkmcnt(0)
	v_mov_b32_e32 v5, v4
	v_mov_b64_e32 v[6:7], 0
	v_mov_b64_e32 v[8:9], 0
	v_mov_b64_e32 v[10:11], 0
	v_mov_b64_e32 v[20:21], 0
	v_mov_b64_e32 v[22:23], 0
	v_mov_b64_e32 v[24:25], 0
	v_mov_b64_e32 v[26:27], 0
	v_mov_b64_e32 v[36:37], 0
	v_mov_b64_e32 v[38:39], 0
	v_mov_b64_e32 v[40:41], 0
	v_mov_b64_e32 v[42:43], 0
	v_mov_b64_e32 v[52:53], 0
	v_mov_b64_e32 v[54:55], 0
	v_mov_b64_e32 v[56:57], 0
	v_mov_b64_e32 v[58:59], 0
	v_mov_b64_e32 v[12:13], 0
	v_mov_b64_e32 v[14:15], 0
	v_mov_b64_e32 v[16:17], 0
	v_mov_b64_e32 v[18:19], 0
	v_mov_b64_e32 v[28:29], 0
	v_mov_b64_e32 v[30:31], 0
	v_mov_b64_e32 v[32:33], 0
	v_mov_b64_e32 v[34:35], 0
	v_mov_b64_e32 v[44:45], 0
	v_mov_b64_e32 v[46:47], 0
	v_mov_b64_e32 v[48:49], 0
	v_mov_b64_e32 v[50:51], 0
	v_mov_b64_e32 v[60:61], 0
	v_mov_b64_e32 v[62:63], 0
	v_mov_b64_e32 v[64:65], 0
	v_mov_b64_e32 v[66:67], 0
	v_mov_b64_e32 v[68:69], 0
	v_mov_b64_e32 v[70:71], 0
	v_mov_b64_e32 v[72:73], 0
	v_mov_b64_e32 v[74:75], 0
	v_mov_b64_e32 v[84:85], 0
	v_mov_b64_e32 v[86:87], 0
	v_mov_b64_e32 v[88:89], 0
	v_mov_b64_e32 v[90:91], 0
	v_mov_b64_e32 v[100:101], 0
	v_mov_b64_e32 v[102:103], 0
	v_mov_b64_e32 v[104:105], 0
	v_mov_b64_e32 v[106:107], 0
	v_mov_b64_e32 v[116:117], 0
	v_mov_b64_e32 v[118:119], 0
	v_mov_b64_e32 v[120:121], 0
	v_mov_b64_e32 v[122:123], 0
	v_mov_b64_e32 v[76:77], 0
	v_mov_b64_e32 v[78:79], 0
	v_mov_b64_e32 v[80:81], 0
	v_mov_b64_e32 v[82:83], 0
	v_mov_b64_e32 v[92:93], 0
	v_mov_b64_e32 v[94:95], 0
	v_mov_b64_e32 v[96:97], 0
	v_mov_b64_e32 v[98:99], 0
	v_mov_b64_e32 v[108:109], 0
	v_mov_b64_e32 v[110:111], 0
	v_mov_b64_e32 v[112:113], 0
	v_mov_b64_e32 v[114:115], 0
	v_mov_b64_e32 v[124:125], 0
	v_mov_b64_e32 v[126:127], 0
	v_mov_b64_e32 v[128:129], 0
	v_mov_b64_e32 v[130:131], 0
	s_waitcnt vmcnt(0)

.LBB0_3087:
	v_and_b32_e32 v3, 15, v1
	v_and_b32_e32 v4, 48, v1
	v_lshlrev_b32_e32 v3, 6, v3
	v_lshlrev_b32_e32 v1, 2, v1
	v_or_b32_e32 v5, v3, v4
	v_and_b32_e32 v1, 32, v1
	s_lshl_b32 s16, s16, 12
	s_lshl_b32 s15, s15, 13
	v_bitop3_b32 v6, v5, s15, v1 bitop3:0xde
	s_and_b32 s15, s16, 0x3000
	s_add_u32 s16, s6, 0x80
	v_mov_b32_e32 v133, v2
	s_addc_u32 s17, s7, 0
	v_bitop3_b32 v3, v3, v1, v4 bitop3:0x36
	s_waitcnt vmcnt(2)
	s_barrier
	s_add_i32 m0, s41, 0x18000
	v_lshl_add_u64 v[4:5], s[16:17], 0, v[132:133]
	v_mov_b32_e32 v135, v2
	global_load_lds_dwordx4 v[4:5], off
	s_add_i32 m0, s41, 0x1a000
	v_lshl_add_u64 v[4:5], s[16:17], 0, v[134:135]
	s_add_u32 s16, s38, 0x12ddec80
	s_addc_u32 s17, s39, 0
	s_add_i32 s38, s41, 0x8000
	global_load_lds_dwordx4 v[4:5], off
	s_mov_b32 m0, s38
	v_lshl_add_u64 v[4:5], s[16:17], 0, v[132:133]
	s_add_i32 s39, s41, 0xa000
	global_load_lds_dwordx4 v[4:5], off
	v_lshl_add_u64 v[4:5], s[16:17], 0, v[134:135]
	s_add_u32 s16, s6, 0xb0080
	s_mov_b32 m0, s39
	s_addc_u32 s17, s7, 0
	global_load_lds_dwordx4 v[4:5], off
	s_add_i32 m0, s41, 0x1c000
	v_lshl_add_u64 v[4:5], s[16:17], 0, v[132:133]
	global_load_lds_dwordx4 v[4:5], off
	v_lshl_add_u64 v[4:5], s[16:17], 0, v[134:135]
	s_add_i32 m0, s41, 0x1e000
	v_or_b32_e32 v1, s15, v3
	global_load_lds_dwordx4 v[4:5], off
	s_waitcnt vmcnt(6)
	v_readlane_b32 s15, v254, 29
	s_add_u32 s45, s15, s40
	v_readlane_b32 s15, v254, 28
	v_mov_b32_e32 v4, 0
	s_addc_u32 s46, s15, s14
	s_mov_b32 s47, -2
	v_add_u32_e32 v3, 0, v6
	s_mov_b64 s[14:15], s[0:1]
	v_mov_b32_e32 v5, v4
	v_mov_b64_e32 v[6:7], 0
	v_mov_b64_e32 v[8:9], 0
	v_mov_b64_e32 v[10:11], 0
	v_mov_b64_e32 v[20:21], 0
	v_mov_b64_e32 v[22:23], 0
	v_mov_b64_e32 v[24:25], 0
	v_mov_b64_e32 v[26:27], 0
	v_mov_b64_e32 v[36:37], 0
	v_mov_b64_e32 v[38:39], 0
	v_mov_b64_e32 v[40:41], 0
	v_mov_b64_e32 v[42:43], 0
	v_mov_b64_e32 v[52:53], 0
	v_mov_b64_e32 v[54:55], 0
	v_mov_b64_e32 v[56:57], 0
	v_mov_b64_e32 v[58:59], 0
	v_mov_b64_e32 v[12:13], 0
	v_mov_b64_e32 v[14:15], 0
	v_mov_b64_e32 v[16:17], 0
	v_mov_b64_e32 v[18:19], 0
	v_mov_b64_e32 v[28:29], 0
	v_mov_b64_e32 v[30:31], 0
	v_mov_b64_e32 v[32:33], 0
	v_mov_b64_e32 v[34:35], 0
	v_mov_b64_e32 v[44:45], 0
	v_mov_b64_e32 v[46:47], 0
	v_mov_b64_e32 v[48:49], 0
	v_mov_b64_e32 v[50:51], 0
	v_mov_b64_e32 v[60:61], 0
	v_mov_b64_e32 v[62:63], 0
	v_mov_b64_e32 v[64:65], 0
	v_mov_b64_e32 v[66:67], 0
	v_mov_b64_e32 v[68:69], 0
	v_mov_b64_e32 v[70:71], 0
	v_mov_b64_e32 v[72:73], 0
	v_mov_b64_e32 v[74:75], 0
	v_mov_b64_e32 v[84:85], 0
	v_mov_b64_e32 v[86:87], 0
	v_mov_b64_e32 v[88:89], 0
	v_mov_b64_e32 v[90:91], 0
	v_mov_b64_e32 v[100:101], 0
	v_mov_b64_e32 v[102:103], 0
	v_mov_b64_e32 v[104:105], 0
	v_mov_b64_e32 v[106:107], 0
	v_mov_b64_e32 v[116:117], 0
	v_mov_b64_e32 v[118:119], 0
	v_mov_b64_e32 v[120:121], 0
	v_mov_b64_e32 v[122:123], 0
	v_mov_b64_e32 v[76:77], 0
	v_mov_b64_e32 v[78:79], 0
	v_mov_b64_e32 v[80:81], 0
	v_mov_b64_e32 v[82:83], 0
	v_mov_b64_e32 v[92:93], 0
	v_mov_b64_e32 v[94:95], 0
	v_mov_b64_e32 v[96:97], 0
	v_mov_b64_e32 v[98:99], 0
	v_mov_b64_e32 v[108:109], 0
	v_mov_b64_e32 v[110:111], 0
	v_mov_b64_e32 v[112:113], 0
	v_mov_b64_e32 v[114:115], 0
	v_mov_b64_e32 v[124:125], 0
	v_mov_b64_e32 v[126:127], 0
	v_mov_b64_e32 v[128:129], 0
	v_mov_b64_e32 v[130:131], 0
	s_barrier
	s_waitcnt vmcnt(0)

.LBB0_3198:
	s_add_u32 s62, s8, 0x100
	v_mov_b32_e32 v4, 0
	s_addc_u32 s63, s9, 0
	s_mov_b32 s64, -2
	s_waitcnt lgkmcnt(0)
	v_mov_b32_e32 v5, v4
	v_mov_b64_e32 v[6:7], 0
	v_mov_b64_e32 v[8:9], 0
	v_mov_b64_e32 v[10:11], 0
	v_mov_b64_e32 v[20:21], 0
	v_mov_b64_e32 v[22:23], 0
	v_mov_b64_e32 v[24:25], 0
	v_mov_b64_e32 v[26:27], 0
	v_mov_b64_e32 v[36:37], 0
	v_mov_b64_e32 v[38:39], 0
	v_mov_b64_e32 v[40:41], 0
	v_mov_b64_e32 v[42:43], 0
	v_mov_b64_e32 v[52:53], 0
	v_mov_b64_e32 v[54:55], 0
	v_mov_b64_e32 v[56:57], 0
	v_mov_b64_e32 v[58:59], 0
	v_mov_b64_e32 v[12:13], 0
	v_mov_b64_e32 v[14:15], 0
	v_mov_b64_e32 v[16:17], 0
	v_mov_b64_e32 v[18:19], 0
	v_mov_b64_e32 v[28:29], 0
	v_mov_b64_e32 v[30:31], 0
	v_mov_b64_e32 v[32:33], 0
	v_mov_b64_e32 v[34:35], 0
	v_mov_b64_e32 v[44:45], 0
	v_mov_b64_e32 v[46:47], 0
	v_mov_b64_e32 v[48:49], 0
	v_mov_b64_e32 v[50:51], 0
	v_mov_b64_e32 v[60:61], 0
	v_mov_b64_e32 v[62:63], 0
	v_mov_b64_e32 v[64:65], 0
	v_mov_b64_e32 v[66:67], 0
	v_mov_b64_e32 v[68:69], 0
	v_mov_b64_e32 v[70:71], 0
	v_mov_b64_e32 v[72:73], 0
	v_mov_b64_e32 v[74:75], 0
	v_mov_b64_e32 v[84:85], 0
	v_mov_b64_e32 v[86:87], 0
	v_mov_b64_e32 v[88:89], 0
	v_mov_b64_e32 v[90:91], 0
	v_mov_b64_e32 v[100:101], 0
	v_mov_b64_e32 v[102:103], 0
	v_mov_b64_e32 v[104:105], 0
	v_mov_b64_e32 v[106:107], 0
	v_mov_b64_e32 v[116:117], 0
	v_mov_b64_e32 v[118:119], 0
	v_mov_b64_e32 v[120:121], 0
	v_mov_b64_e32 v[122:123], 0
	v_mov_b64_e32 v[76:77], 0
	v_mov_b64_e32 v[78:79], 0
	v_mov_b64_e32 v[80:81], 0
	v_mov_b64_e32 v[82:83], 0
	v_mov_b64_e32 v[92:93], 0
	v_mov_b64_e32 v[94:95], 0
	v_mov_b64_e32 v[96:97], 0
	v_mov_b64_e32 v[98:99], 0
	v_mov_b64_e32 v[108:109], 0
	v_mov_b64_e32 v[110:111], 0
	v_mov_b64_e32 v[112:113], 0
	v_mov_b64_e32 v[114:115], 0
	v_mov_b64_e32 v[124:125], 0
	v_mov_b64_e32 v[126:127], 0
	v_mov_b64_e32 v[128:129], 0
	v_mov_b64_e32 v[130:131], 0
